# nt on one-shot activation loads: RMSNorm1 x rows, out_proj and down_proj epilogue residual loads; on v48
# speedup vs baseline: 1.0076x; 1.0076x over previous
; #define LAS __attribute__((address_space(3)))
; __device__ __forceinline__ void norm_mod_stage(Frame& F, const float* gain, int shift_chunk, int scale_chunk) {
;     const float* mod = (const float*)(F.ws + WS_MOD);
;     LAS f32x4* A4 = (LAS f32x4*)(F.lds + RING_OFF); LAS f32x4* S4 = A4 + 2 * (DM / 4);
; #pragma unroll 1
;     for (int b = 0; b < 2; ++b)
; #pragma unroll 1
;         for (int c4 = F.tid; c4 < DM / 4; c4 += NWAVES * 64) {
;             const f32x4 g = ((const f32x4*)gain)[c4], sc = ((const f32x4*)(mod + (size_t)b * NMOD + scale_chunk * DM))[c4], sh = ((const f32x4*)(mod + (size_t)b * NMOD + shift_chunk * DM))[c4];
;             A4[b * (DM / 4) + c4] = g * (1.0f + sc); S4[b * (DM / 4) + c4] = sh; }
;     __syncthreads();
; }
.LBB0_321:
	s_cmp_lt_i32 s86, 3
	s_cselect_b64 s[0:1], -1, 0
	s_cmp_gt_i32 s87, 2
	s_cselect_b64 s[4:5], -1, 0
	s_and_b64 s[0:1], s[0:1], s[4:5]
	s_andn2_b64 vcc, exec, s[0:1]
	s_cbranch_vccnz .LBB0_380
	v_mov_b32_e32 v2, v0
	v_readlane_b32 s12, v252, 2
	v_ashrrev_i32_e32 v3, 31, v2
	s_movk_i32 s0, 0x400
	v_lshlrev_b64 v[4:5], 4, v[2:3]
	v_readlane_b32 s20, v252, 10
	v_readlane_b32 s21, v252, 11
	v_cmp_gt_i32_e64 s[0:1], s0, v2
	v_add_u32_e32 v1, 0xfffffe00, v2
	s_waitcnt vmcnt(0)
	v_lshl_add_u32 v10, v2, 4, 0
	v_lshl_add_u64 v[2:3], s[20:21], 0, v[4:5]
	v_lshl_add_u64 v[4:5], s[82:83], 0, v[4:5]
	s_mov_b64 s[4:5], 0x104000
	s_mov_b32 s10, 0
	v_lshl_add_u64 v[4:5], v[4:5], 0, s[4:5]
	s_mov_b64 s[6:7], -1
	s_mov_b64 s[4:5], 0x2000
	s_movk_i32 s2, 0x1ff
	v_mov_b32_e32 v11, 0x18000
	v_readlane_b32 s13, v252, 3
	v_readlane_b32 s14, v252, 4
	v_readlane_b32 s15, v252, 5
	v_readlane_b32 s16, v252, 6
	v_readlane_b32 s17, v252, 7
	v_readlane_b32 s18, v252, 8
	v_readlane_b32 s19, v252, 9
	v_readlane_b32 s22, v252, 12
	v_readlane_b32 s23, v252, 13
	v_readlane_b32 s24, v252, 14
	v_readlane_b32 s25, v252, 15
	v_readlane_b32 s26, v252, 16
	v_readlane_b32 s27, v252, 17
	v_lshl_add_u64 v[8:9], v[2:3], 0, s[4:5]
	global_load_dwordx4 v[14:17], v[2:3], off nt
	global_load_dwordx4 v[18:21], v[8:9], off nt
	v_lshl_add_u64 v[6:7], v[4:5], 0, s[4:5]
	global_load_dwordx4 v[22:25], v[4:5], off nt
	global_load_dwordx4 v[26:29], v[6:7], off nt
	s_mov_b64 s[8:9], 0x18000
	v_lshl_add_u64 v[54:55], v[4:5], 0, s[8:9]
	v_lshl_add_u64 v[56:57], v[54:55], 0, s[4:5]
	global_load_dwordx4 v[30:33], v[54:55], off nt
	global_load_dwordx4 v[34:37], v[56:57], off nt
	v_add_co_u32_e32 v58, vcc, 0xffffc000, v4
	s_nop 1
	v_addc_co_u32_e32 v59, vcc, -1, v5, vcc
	global_load_dwordx4 v[38:41], v[58:59], off nt
	v_add_co_u32_e32 v58, vcc, 0xffffc000, v6
	s_nop 1
	v_addc_co_u32_e32 v59, vcc, -1, v7, vcc
	global_load_dwordx4 v[42:45], v[58:59], off nt
	v_add_co_u32_e32 v58, vcc, 0xffffc000, v54
	s_nop 1
	v_addc_co_u32_e32 v59, vcc, -1, v55, vcc
	global_load_dwordx4 v[46:49], v[58:59], off nt
	v_add_co_u32_e32 v58, vcc, 0xffffc000, v56
	s_nop 1
	v_addc_co_u32_e32 v59, vcc, -1, v57, vcc
	global_load_dwordx4 v[50:53], v[58:59], off nt
	s_waitcnt vmcnt(4)
	v_pk_add_f32 v[22:23], v[22:23], 1.0 op_sel_hi:[1,0]
	v_pk_add_f32 v[24:25], v[24:25], 1.0 op_sel_hi:[1,0]
	v_pk_add_f32 v[26:27], v[26:27], 1.0 op_sel_hi:[1,0]
	v_pk_add_f32 v[28:29], v[28:29], 1.0 op_sel_hi:[1,0]
	v_pk_add_f32 v[30:31], v[30:31], 1.0 op_sel_hi:[1,0]
	v_pk_add_f32 v[32:33], v[32:33], 1.0 op_sel_hi:[1,0]
	v_pk_add_f32 v[34:35], v[34:35], 1.0 op_sel_hi:[1,0]
	v_pk_add_f32 v[36:37], v[36:37], 1.0 op_sel_hi:[1,0]
	v_pk_mul_f32 v[22:23], v[14:15], v[22:23]
	v_pk_mul_f32 v[24:25], v[16:17], v[24:25]
	v_pk_mul_f32 v[26:27], v[18:19], v[26:27]
	v_pk_mul_f32 v[28:29], v[20:21], v[28:29]
	v_pk_mul_f32 v[30:31], v[14:15], v[30:31]
	v_pk_mul_f32 v[32:33], v[16:17], v[32:33]
	v_pk_mul_f32 v[34:35], v[18:19], v[34:35]
	v_pk_mul_f32 v[36:37], v[20:21], v[36:37]
	ds_write_b128 v10, v[22:25]
	ds_write_b128 v10, v[26:29] offset:8192
	ds_write_b128 v10, v[30:33] offset:16384
	ds_write_b128 v10, v[34:37] offset:24576
	s_waitcnt vmcnt(0)
	ds_write_b128 v10, v[38:41] offset:32768
	ds_write_b128 v10, v[42:45] offset:40960
	ds_write_b128 v10, v[46:49] offset:49152
	ds_write_b128 v10, v[50:53] offset:57344

; #define GAS __attribute__((address_space(1)))
; __device__ __forceinline__ void norm_mod_rows(Frame& F, const float* src, int ldh) {
;     ...
;     for (int row = gw; row < M; row += NGW) {
;         const int b = row / SEQ;
;         const GAS f32x4* xr = (const GAS f32x4*)(src + (size_t)row * DM) + F.lane;
;         f32x4 v[16]; float ss = 0.f;
; #pragma unroll
;         for (int j = 0; j < 16; ++j) { v[j] = xr[64 * j]; ss += (v[j].x * v[j].x + v[j].y * v[j].y) + (v[j].z * v[j].z + v[j].w * v[j].w); }
;         const float rstd = 1.0f / sqrtf(wave_sum(ss) * (1.0f / DM) + EPS);
.LBB0_329:
	global_load_dwordx4 v[2:5], v[68:69], off nt
	global_load_dwordx4 v[6:9], v[68:69], off offset:1024 nt
	global_load_dwordx4 v[10:13], v[68:69], off offset:2048 nt
	global_load_dwordx4 v[14:17], v[68:69], off offset:3072 nt
	v_add_co_u32_e32 v20, vcc, s5, v68
	s_ashr_i32 s0, s2, 31
	s_nop 0
	v_addc_co_u32_e32 v21, vcc, 0, v69, vcc
	v_add_co_u32_e32 v18, vcc, s10, v68
	s_lshr_b32 s0, s0, 20
	s_nop 0
	v_addc_co_u32_e32 v19, vcc, 0, v69, vcc
	v_add_co_u32_e32 v30, vcc, s11, v68
	s_add_i32 s0, s2, s0
	s_nop 0
	v_addc_co_u32_e32 v31, vcc, 0, v69, vcc
	global_load_dwordx4 v[58:61], v[18:19], off offset:-4096 nt
	global_load_dwordx4 v[46:49], v[20:21], off offset:2048 nt
	global_load_dwordx4 v[62:65], v[20:21], off offset:1024 nt
	global_load_dwordx4 v[50:53], v[20:21], off offset:3072 nt
	global_load_dwordx4 v[34:37], v[18:19], off offset:1024 nt
	global_load_dwordx4 v[54:57], v[18:19], off nt
	global_load_dwordx4 v[38:41], v[18:19], off offset:2048 nt
	global_load_dwordx4 v[22:25], v[30:31], off nt
	global_load_dwordx4 v[42:45], v[18:19], off offset:3072 nt
	global_load_dwordx4 v[26:29], v[30:31], off offset:1024 nt
	s_nop 0
	global_load_dwordx4 v[18:21], v[30:31], off offset:3072 nt
	s_nop 0
	global_load_dwordx4 v[30:33], v[30:31], off offset:2048 nt
	s_lshl_b32 s0, s0, 2
	s_and_b32 s0, s0, 0xffffc000
	v_add_u32_e32 v153, s0, v77
	v_add_co_u32_e32 v70, vcc, s5, v66
	ds_read_b128 v[80:83], v153 offset:32768
	ds_read_b128 v[84:87], v153 offset:33792
	ds_read_b128 v[88:91], v153
	ds_read_b128 v[92:95], v153 offset:1024
	ds_read_b128 v[96:99], v153 offset:34816
	ds_read_b128 v[100:103], v153 offset:35840
	ds_read_b128 v[104:107], v153 offset:2048
	ds_read_b128 v[108:111], v153 offset:3072
	v_addc_co_u32_e32 v71, vcc, 0, v67, vcc
	s_add_i32 s2, s2, s4
	v_lshl_add_u64 v[68:69], v[68:69], 0, s[8:9]
	s_cmpk_lt_i32 s2, 0x2000
	s_waitcnt vmcnt(15)
	v_pk_mul_f32 v[112:113], v[4:5], v[4:5]
	v_pk_mul_f32 v[114:115], v[2:3], v[2:3]
	s_waitcnt vmcnt(14)
	v_pk_mul_f32 v[116:117], v[8:9], v[8:9]
	v_pk_mul_f32 v[118:119], v[6:7], v[6:7]
	v_pk_mov_b32 v[124:125], v[114:115], v[112:113] op_sel:[1,0]
	v_mov_b32_e32 v115, v113
	v_pk_mov_b32 v[112:113], v[118:119], v[116:117] op_sel:[1,0]
	v_mov_b32_e32 v119, v117
	s_waitcnt vmcnt(13)
	v_mul_f32_e32 v120, v11, v11
	v_mul_f32_e32 v122, v13, v13
	v_pk_add_f32 v[114:115], v[124:125], v[114:115]
	v_pk_add_f32 v[112:113], v[112:113], v[118:119]
	s_waitcnt vmcnt(12)
	v_mul_f32_e32 v155, v14, v14
	v_mul_f32_e32 v156, v15, v15
	v_mul_f32_e32 v129, v16, v16
	v_mul_f32_e32 v131, v17, v17
	v_pk_fma_f32 v[116:117], v[10:11], v[10:11], v[120:121] op_sel_hi:[1,1,0]
	v_pk_fma_f32 v[120:121], v[12:13], v[12:13], v[122:123] op_sel_hi:[1,1,0]
	v_pk_add_f32 v[114:115], v[114:115], v[114:115] op_sel:[0,1] op_sel_hi:[1,0]
	v_pk_add_f32 v[112:113], v[112:113], v[112:113] op_sel:[0,1] op_sel_hi:[1,0]
	s_waitcnt vmcnt(11)
	v_pk_mul_f32 v[122:123], v[60:61], v[60:61]
	v_pk_mul_f32 v[126:127], v[58:59], v[58:59]
	v_mov_b32_e32 v117, v129
	v_mov_b32_e32 v121, v131
	v_mov_b32_e32 v115, v155
	v_mov_b32_e32 v113, v156
	v_pk_mov_b32 v[118:119], v[126:127], v[122:123] op_sel:[1,0]
	v_mov_b32_e32 v127, v123
	v_pk_add_f32 v[116:117], v[116:117], v[120:121]
	v_pk_add_f32 v[112:113], v[114:115], v[112:113]
	s_waitcnt vmcnt(9)
	v_mul_f32_e32 v128, v63, v63
	v_mul_f32_e32 v130, v65, v65
	v_pk_add_f32 v[118:119], v[118:119], v[126:127]
	v_pk_add_f32 v[112:113], v[112:113], v[116:117]
	v_mul_f32_e32 v157, v46, v46
	v_mul_f32_e32 v158, v47, v47
	v_mul_f32_e32 v159, v48, v48
	v_mul_f32_e32 v160, v49, v49
	v_pk_fma_f32 v[122:123], v[62:63], v[62:63], v[128:129] op_sel_hi:[1,1,0]
	v_pk_fma_f32 v[124:125], v[64:65], v[64:65], v[130:131] op_sel_hi:[1,1,0]
	v_pk_add_f32 v[118:119], v[118:119], v[118:119] op_sel:[0,1] op_sel_hi:[1,0]
	v_pk_add_f32 v[112:113], v[112:113], v[112:113] op_sel:[0,1] op_sel_hi:[1,0]
	s_waitcnt vmcnt(8)
	v_pk_mul_f32 v[132:133], v[52:53], v[52:53]
	v_pk_mul_f32 v[134:135], v[50:51], v[50:51]
	v_mov_b32_e32 v123, v159
	v_mov_b32_e32 v125, v160
	v_mov_b32_e32 v119, v158
	v_mov_b32_e32 v113, v157
	v_pk_mov_b32 v[128:129], v[134:135], v[132:133] op_sel:[1,0]
	v_mov_b32_e32 v135, v133
	v_pk_add_f32 v[122:123], v[122:123], v[124:125]
	v_pk_add_f32 v[112:113], v[112:113], v[118:119]
	s_waitcnt vmcnt(6)
	v_mul_f32_e32 v136, v55, v55
	v_mul_f32_e32 v138, v57, v57
	v_pk_add_f32 v[120:121], v[128:129], v[134:135]
	v_pk_add_f32 v[112:113], v[112:113], v[122:123]
	v_mul_f32_e32 v161, v34, v34
	v_mul_f32_e32 v162, v35, v35
	v_mul_f32_e32 v163, v36, v36
	v_mul_f32_e32 v164, v37, v37
	v_pk_fma_f32 v[130:131], v[54:55], v[54:55], v[136:137] op_sel_hi:[1,1,0]
	v_pk_fma_f32 v[132:133], v[56:57], v[56:57], v[138:139] op_sel_hi:[1,1,0]
	v_pk_add_f32 v[120:121], v[120:121], v[120:121] op_sel:[0,1] op_sel_hi:[1,0]
	v_pk_add_f32 v[112:113], v[112:113], v[112:113] op_sel:[0,1] op_sel_hi:[1,0]
	s_waitcnt vmcnt(5)
	v_pk_mul_f32 v[140:141], v[40:41], v[40:41]
	v_pk_mul_f32 v[142:143], v[38:39], v[38:39]
	v_mov_b32_e32 v131, v163
	v_mov_b32_e32 v133, v164
	v_mov_b32_e32 v121, v162
	v_mov_b32_e32 v113, v161
	v_pk_mov_b32 v[136:137], v[142:143], v[140:141] op_sel:[1,0]
	v_mov_b32_e32 v143, v141
	v_pk_add_f32 v[124:125], v[130:131], v[132:133]
	v_pk_add_f32 v[112:113], v[112:113], v[120:121]
	s_waitcnt vmcnt(3)
	v_mul_f32_e32 v144, v43, v43
	v_mul_f32_e32 v146, v45, v45
	v_pk_add_f32 v[126:127], v[136:137], v[142:143]
	v_pk_add_f32 v[112:113], v[112:113], v[124:125]
	v_mul_f32_e32 v165, v22, v22
	v_mul_f32_e32 v166, v23, v23
	v_mul_f32_e32 v167, v24, v24
	v_mul_f32_e32 v168, v25, v25
	v_pk_fma_f32 v[138:139], v[42:43], v[42:43], v[144:145] op_sel_hi:[1,1,0]
	v_pk_fma_f32 v[140:141], v[44:45], v[44:45], v[146:147] op_sel_hi:[1,1,0]
	v_pk_add_f32 v[126:127], v[126:127], v[126:127] op_sel:[0,1] op_sel_hi:[1,0]
	v_pk_add_f32 v[112:113], v[112:113], v[112:113] op_sel:[0,1] op_sel_hi:[1,0]
	s_waitcnt vmcnt(2)
; #define GAS __attribute__((address_space(1)))
; #define LAS __attribute__((address_space(3)))
; __device__ __forceinline__ unsigned pk2(float lo, float hi) { pkf32x2 v = {lo, hi}; pkbf16x2 b = __builtin_convertvector(v, pkbf16x2); return __builtin_bit_cast(unsigned, b); }
; __device__ __forceinline__ void norm_mod_rows(Frame& F, const float* src, int ldh) {
;     ...
;         const float rstd = 1.0f / sqrtf(wave_sum(ss) * (1.0f / DM) + EPS);
;         const LAS f32x4* ap = A4 + b * (DM / 4) + F.lane; const LAS f32x4* sp = S4 + b * (DM / 4) + F.lane;
;         GAS v2u* o8 = (GAS v2u*)(H + (size_t)row * ldh) + F.lane;
; #pragma unroll
;         for (int j = 0; j < 16; ++j) { const f32x4 y = (v[j] * rstd) * ap[64 * j] + sp[64 * j];
;             v2u w; w.x = pk2(y.x, y.y); w.y = pk2(y.z, y.w); o8[64 * j] = w;
;             if ((j & 3) == 3) asm volatile("" ::: "memory"); }
	v_pk_mul_f32 v[148:149], v[28:29], v[28:29]
	v_pk_mul_f32 v[150:151], v[26:27], v[26:27]
	v_mov_b32_e32 v139, v167
	v_mov_b32_e32 v141, v168
	v_mov_b32_e32 v127, v166
	v_mov_b32_e32 v113, v165
	v_pk_mov_b32 v[144:145], v[150:151], v[148:149] op_sel:[1,0]
	v_mov_b32_e32 v151, v149
	v_pk_add_f32 v[130:131], v[138:139], v[140:141]
	v_pk_add_f32 v[112:113], v[112:113], v[126:127]
	s_waitcnt vmcnt(0)
	v_mul_f32_e32 v152, v31, v31
	v_mul_f32_e32 v154, v33, v33
	v_pk_add_f32 v[128:129], v[144:145], v[150:151]
	v_pk_add_f32 v[112:113], v[112:113], v[130:131]
	v_mul_f32_e32 v169, v18, v18
	v_mul_f32_e32 v170, v19, v19
	v_mul_f32_e32 v171, v20, v20
	v_mul_f32_e32 v172, v21, v21
	v_pk_fma_f32 v[146:147], v[30:31], v[30:31], v[152:153] op_sel_hi:[1,1,0]
	v_pk_fma_f32 v[148:149], v[32:33], v[32:33], v[154:155] op_sel_hi:[1,1,0]
	v_pk_add_f32 v[128:129], v[128:129], v[128:129] op_sel:[0,1] op_sel_hi:[1,0]
	v_pk_add_f32 v[112:113], v[112:113], v[112:113] op_sel:[0,1] op_sel_hi:[1,0]
	v_mov_b32_e32 v147, v171
	v_mov_b32_e32 v149, v172
	v_mov_b32_e32 v129, v170
	v_mov_b32_e32 v113, v169
	v_pk_add_f32 v[132:133], v[146:147], v[148:149]
	v_pk_add_f32 v[112:113], v[112:113], v[128:129]
	s_nop 0
	v_pk_add_f32 v[112:113], v[112:113], v[132:133]
	s_nop 0
	v_add_f32_e32 v112, v112, v113
	ds_bpermute_b32 v113, v1, v112
	s_waitcnt lgkmcnt(0)
	v_add_f32_e32 v112, v112, v113
	ds_bpermute_b32 v113, v72, v112
	s_waitcnt lgkmcnt(0)
	v_add_f32_e32 v112, v112, v113
	ds_bpermute_b32 v113, v73, v112
	s_waitcnt lgkmcnt(0)
	v_add_f32_e32 v112, v112, v113
	ds_bpermute_b32 v113, v74, v112
	s_waitcnt lgkmcnt(0)
	v_add_f32_e32 v112, v112, v113
	ds_bpermute_b32 v113, v75, v112
	s_waitcnt lgkmcnt(0)
	v_add_f32_e32 v112, v112, v113
	ds_bpermute_b32 v113, v76, v112
	s_waitcnt lgkmcnt(0)
	v_add_f32_e32 v112, v112, v113
	v_fmamk_f32 v112, v112, 0x39800000, v78
	v_mul_f32_e32 v113, 0x4f800000, v112
	v_cmp_gt_f32_e32 vcc, s12, v112
	s_nop 1
	v_cndmask_b32_e32 v112, v112, v113, vcc
	v_sqrt_f32_e32 v113, v112
	s_nop 0
	v_add_u32_e32 v114, -1, v113
	v_add_u32_e32 v115, 1, v113
	v_fma_f32 v116, -v114, v113, v112
	v_fma_f32 v117, -v115, v113, v112
	v_cmp_ge_f32_e64 s[0:1], 0, v116
	s_nop 1
	v_cndmask_b32_e64 v113, v113, v114, s[0:1]
	v_cmp_lt_f32_e64 s[0:1], 0, v117
	s_nop 1
	v_cndmask_b32_e64 v113, v113, v115, s[0:1]
	v_mul_f32_e32 v114, 0x37800000, v113
	v_cndmask_b32_e32 v113, v113, v114, vcc
	v_cmp_class_f32_e32 vcc, v112, v79
	s_nop 1
	v_cndmask_b32_e32 v112, v113, v112, vcc
	v_div_scale_f32 v113, s[0:1], v112, v112, 1.0
	v_rcp_f32_e32 v115, v113
	v_div_scale_f32 v114, vcc, 1.0, v112, 1.0
	v_fma_f32 v116, -v113, v115, 1.0
	v_fmac_f32_e32 v115, v116, v115
	v_mul_f32_e32 v116, v114, v115
	v_fma_f32 v117, -v113, v116, v114
	v_fmac_f32_e32 v116, v117, v115
	v_fma_f32 v113, -v113, v116, v114
	v_div_fmas_f32 v113, v113, v115, v116
	v_div_fixup_f32 v112, v113, v112, 1.0
	v_pk_mul_f32 v[2:3], v[2:3], v[112:113] op_sel_hi:[1,0]
	v_pk_mul_f32 v[4:5], v[4:5], v[112:113] op_sel_hi:[1,0]
	v_pk_mul_f32 v[6:7], v[6:7], v[112:113] op_sel_hi:[1,0]
	v_pk_mul_f32 v[8:9], v[8:9], v[112:113] op_sel_hi:[1,0]
	v_pk_mul_f32 v[10:11], v[10:11], v[112:113] op_sel_hi:[1,0]
	v_pk_mul_f32 v[12:13], v[12:13], v[112:113] op_sel_hi:[1,0]
	v_pk_mul_f32 v[14:15], v[14:15], v[112:113] op_sel_hi:[1,0]
	v_pk_mul_f32 v[16:17], v[16:17], v[112:113] op_sel_hi:[1,0]
	v_pk_fma_f32 v[4:5], v[90:91], v[4:5], v[82:83]
	v_pk_fma_f32 v[2:3], v[88:89], v[2:3], v[80:81]
	v_pk_fma_f32 v[8:9], v[94:95], v[8:9], v[86:87]
	v_pk_fma_f32 v[6:7], v[92:93], v[6:7], v[84:85]
	v_pk_fma_f32 v[12:13], v[106:107], v[12:13], v[98:99]
	v_pk_fma_f32 v[10:11], v[104:105], v[10:11], v[96:97]
	v_pk_fma_f32 v[16:17], v[110:111], v[16:17], v[102:103]
	v_pk_fma_f32 v[14:15], v[108:109], v[14:15], v[100:101]
	v_cvt_pk_bf16_f32 v2, v2, v3
	v_cvt_pk_bf16_f32 v3, v4, v5
	v_cvt_pk_bf16_f32 v4, v6, v7
	v_cvt_pk_bf16_f32 v5, v8, v9
	v_cvt_pk_bf16_f32 v6, v10, v11
	v_cvt_pk_bf16_f32 v7, v12, v13
	v_cvt_pk_bf16_f32 v8, v14, v15
	v_cvt_pk_bf16_f32 v9, v16, v17
	global_store_dwordx2 v[66:67], v[2:3], off
	global_store_dwordx2 v[66:67], v[4:5], off offset:512
	global_store_dwordx2 v[66:67], v[6:7], off offset:1024
	global_store_dwordx2 v[66:67], v[8:9], off offset:1536
	v_pk_mul_f32 v[58:59], v[58:59], v[112:113] op_sel_hi:[1,0]
	v_pk_mul_f32 v[60:61], v[60:61], v[112:113] op_sel_hi:[1,0]
	v_pk_mul_f32 v[62:63], v[62:63], v[112:113] op_sel_hi:[1,0]
	v_pk_mul_f32 v[64:65], v[64:65], v[112:113] op_sel_hi:[1,0]
	v_pk_mul_f32 v[46:47], v[46:47], v[112:113] op_sel_hi:[1,0]
	v_pk_mul_f32 v[48:49], v[48:49], v[112:113] op_sel_hi:[1,0]
	v_pk_mul_f32 v[50:51], v[50:51], v[112:113] op_sel_hi:[1,0]
	v_pk_mul_f32 v[52:53], v[52:53], v[112:113] op_sel_hi:[1,0]
	v_pk_mul_f32 v[54:55], v[54:55], v[112:113] op_sel_hi:[1,0]
	v_pk_mul_f32 v[56:57], v[56:57], v[112:113] op_sel_hi:[1,0]
	v_pk_mul_f32 v[34:35], v[34:35], v[112:113] op_sel_hi:[1,0]
	v_pk_mul_f32 v[36:37], v[36:37], v[112:113] op_sel_hi:[1,0]
	v_pk_mul_f32 v[38:39], v[38:39], v[112:113] op_sel_hi:[1,0]
	v_pk_mul_f32 v[40:41], v[40:41], v[112:113] op_sel_hi:[1,0]
	v_pk_mul_f32 v[42:43], v[42:43], v[112:113] op_sel_hi:[1,0]
	v_pk_mul_f32 v[44:45], v[44:45], v[112:113] op_sel_hi:[1,0]
	v_pk_mul_f32 v[114:115], v[22:23], v[112:113] op_sel_hi:[1,0]
	v_pk_mul_f32 v[116:117], v[24:25], v[112:113] op_sel_hi:[1,0]
	v_pk_mul_f32 v[118:119], v[26:27], v[112:113] op_sel_hi:[1,0]
	v_pk_mul_f32 v[120:121], v[28:29], v[112:113] op_sel_hi:[1,0]
	v_pk_mul_f32 v[122:123], v[30:31], v[112:113] op_sel_hi:[1,0]
	v_pk_mul_f32 v[124:125], v[32:33], v[112:113] op_sel_hi:[1,0]
	v_pk_mul_f32 v[126:127], v[18:19], v[112:113] op_sel_hi:[1,0]
	v_pk_mul_f32 v[112:113], v[20:21], v[112:113] op_sel_hi:[1,0]
	ds_read_b128 v[2:5], v153 offset:36864
	ds_read_b128 v[6:9], v153 offset:37888
	ds_read_b128 v[10:13], v153 offset:4096
	ds_read_b128 v[14:17], v153 offset:5120
	ds_read_b128 v[18:21], v153 offset:38912
	ds_read_b128 v[22:25], v153 offset:39936
	ds_read_b128 v[26:29], v153 offset:6144
	ds_read_b128 v[30:33], v153 offset:7168
	s_waitcnt lgkmcnt(5)
; __device__ __forceinline__ unsigned pk2(float lo, float hi) { pkf32x2 v = {lo, hi}; pkbf16x2 b = __builtin_convertvector(v, pkbf16x2); return __builtin_bit_cast(unsigned, b); }
; __device__ __forceinline__ void norm_mod_rows(Frame& F, const float* src, int ldh) {
;     ...
; #pragma unroll
;         for (int j = 0; j < 16; ++j) { const f32x4 y = (v[j] * rstd) * ap[64 * j] + sp[64 * j];
;             v2u w; w.x = pk2(y.x, y.y); w.y = pk2(y.z, y.w); o8[64 * j] = w;
;             if ((j & 3) == 3) asm volatile("" ::: "memory"); }
;     }
	v_pk_fma_f32 v[4:5], v[60:61], v[12:13], v[4:5]
	v_pk_fma_f32 v[2:3], v[58:59], v[10:11], v[2:3]
	s_waitcnt lgkmcnt(4)
	v_pk_fma_f32 v[8:9], v[64:65], v[16:17], v[8:9]
	v_pk_fma_f32 v[6:7], v[62:63], v[14:15], v[6:7]
	s_waitcnt lgkmcnt(1)
	v_pk_fma_f32 v[10:11], v[48:49], v[28:29], v[20:21]
	v_pk_fma_f32 v[12:13], v[46:47], v[26:27], v[18:19]
	s_waitcnt lgkmcnt(0)
	v_pk_fma_f32 v[14:15], v[52:53], v[32:33], v[24:25]
	v_pk_fma_f32 v[16:17], v[50:51], v[30:31], v[22:23]
	v_cvt_pk_bf16_f32 v2, v2, v3
	v_cvt_pk_bf16_f32 v3, v4, v5
	v_cvt_pk_bf16_f32 v4, v6, v7
	v_cvt_pk_bf16_f32 v5, v8, v9
	v_cvt_pk_bf16_f32 v6, v12, v13
	v_cvt_pk_bf16_f32 v7, v10, v11
	v_cvt_pk_bf16_f32 v8, v16, v17
	v_cvt_pk_bf16_f32 v9, v14, v15
	global_store_dwordx2 v[66:67], v[2:3], off offset:2048
	global_store_dwordx2 v[66:67], v[4:5], off offset:2560
	global_store_dwordx2 v[66:67], v[6:7], off offset:3072
	global_store_dwordx2 v[66:67], v[8:9], off offset:3584
	ds_read_b128 v[2:5], v153 offset:40960
	ds_read_b128 v[6:9], v153 offset:41984
	ds_read_b128 v[10:13], v153 offset:8192
	ds_read_b128 v[14:17], v153 offset:9216
	ds_read_b128 v[18:21], v153 offset:43008
	ds_read_b128 v[22:25], v153 offset:44032
	ds_read_b128 v[26:29], v153 offset:10240
	ds_read_b128 v[30:33], v153 offset:11264
	s_waitcnt lgkmcnt(5)
	v_pk_fma_f32 v[4:5], v[56:57], v[12:13], v[4:5]
	v_pk_fma_f32 v[2:3], v[54:55], v[10:11], v[2:3]
	s_waitcnt lgkmcnt(4)
	v_pk_fma_f32 v[8:9], v[36:37], v[16:17], v[8:9]
	v_pk_fma_f32 v[6:7], v[34:35], v[14:15], v[6:7]
	s_waitcnt lgkmcnt(1)
	v_pk_fma_f32 v[10:11], v[40:41], v[28:29], v[20:21]
	v_pk_fma_f32 v[12:13], v[38:39], v[26:27], v[18:19]
	s_waitcnt lgkmcnt(0)
	v_pk_fma_f32 v[14:15], v[44:45], v[32:33], v[24:25]
	v_pk_fma_f32 v[16:17], v[42:43], v[30:31], v[22:23]
	v_cvt_pk_bf16_f32 v2, v2, v3
	v_cvt_pk_bf16_f32 v3, v4, v5
	v_cvt_pk_bf16_f32 v4, v6, v7
	v_cvt_pk_bf16_f32 v5, v8, v9
	v_cvt_pk_bf16_f32 v6, v12, v13
	v_cvt_pk_bf16_f32 v7, v10, v11
	v_cvt_pk_bf16_f32 v8, v16, v17
	v_cvt_pk_bf16_f32 v9, v14, v15
	global_store_dwordx2 v[70:71], v[2:3], off
	global_store_dwordx2 v[70:71], v[4:5], off offset:512
	global_store_dwordx2 v[70:71], v[6:7], off offset:1024
	global_store_dwordx2 v[70:71], v[8:9], off offset:1536
	ds_read_b128 v[2:5], v153 offset:45056
	ds_read_b128 v[6:9], v153 offset:46080
	ds_read_b128 v[10:13], v153 offset:12288
	ds_read_b128 v[14:17], v153 offset:13312
	ds_read_b128 v[18:21], v153 offset:47104
	ds_read_b128 v[22:25], v153 offset:48128
	ds_read_b128 v[26:29], v153 offset:14336
	ds_read_b128 v[30:33], v153 offset:15360
	s_waitcnt lgkmcnt(5)
	v_pk_fma_f32 v[4:5], v[116:117], v[12:13], v[4:5]
	v_pk_fma_f32 v[2:3], v[114:115], v[10:11], v[2:3]
	s_waitcnt lgkmcnt(4)
	v_pk_fma_f32 v[8:9], v[120:121], v[16:17], v[8:9]
	v_pk_fma_f32 v[6:7], v[118:119], v[14:15], v[6:7]
	s_waitcnt lgkmcnt(1)
	v_pk_fma_f32 v[10:11], v[124:125], v[28:29], v[20:21]
	v_pk_fma_f32 v[12:13], v[122:123], v[26:27], v[18:19]
	s_waitcnt lgkmcnt(0)
	v_pk_fma_f32 v[14:15], v[112:113], v[32:33], v[24:25]
	v_pk_fma_f32 v[16:17], v[126:127], v[30:31], v[22:23]
	v_cvt_pk_bf16_f32 v2, v2, v3
	v_cvt_pk_bf16_f32 v3, v4, v5
	v_cvt_pk_bf16_f32 v4, v6, v7
	v_cvt_pk_bf16_f32 v5, v8, v9
	v_cvt_pk_bf16_f32 v6, v12, v13
	v_cvt_pk_bf16_f32 v7, v10, v11
	v_cvt_pk_bf16_f32 v8, v16, v17
	v_cvt_pk_bf16_f32 v9, v14, v15
	global_store_dwordx2 v[70:71], v[2:3], off offset:2048
	global_store_dwordx2 v[70:71], v[4:5], off offset:2560
	global_store_dwordx2 v[70:71], v[6:7], off offset:3072
	global_store_dwordx2 v[70:71], v[8:9], off offset:3584
	v_lshl_add_u64 v[66:67], v[66:67], 0, s[6:7]
	s_cbranch_scc1 .LBB0_329

; __device__ __forceinline__ unsigned cvt_pk_bf16(float lo, float hi) { unsigned r; asm volatile("v_cvt_pk_bf16_f32 %0, %1, %2" : "=v"(r) : "v"(lo), "v"(hi)); return r; }
;     __device__ __forceinline__ void operator()(const f32x4 (&acc)[2][2][4][2], const Unit& u, int wr, int wc, int fr, int fq) const {
;         const int col0 = u.pn * BM + wc * 32 + 8 * fq;
;         const int b = (u.pm * BM) / rows_per_batch;
;         const float* gp = gate + (size_t)b * gate_stride + col0;
;         f32x4 gv[2][2];
; #pragma unroll
;         for (int bj = 0; bj < 2; ++bj)
; #pragma unroll
;             for (int n = 0; n < 2; ++n) gv[bj][n] = *(const f32x4*)(gp + bj * HALF + 4 * n);
;         const size_t row0 = (size_t)(u.pm * BM + wr * 64 + fr) * ldc + col0;
;         f32x4 bs[2][2][2];
; #pragma unroll
;         for (int bj = 0; bj < 2; ++bj)
; #pragma unroll
;             for (int n = 0; n < 2; ++n) bs[0][bj][n] = *(const f32x4*)(base + row0 + bj * HALF + 4 * n);
; #pragma unroll
;         for (int g = 0; g < 8; ++g) { const int ai = g >> 2, m = g & 3; const size_t off = row0 + (size_t)(ai * HALF + m * 16) * ldc;
;             if (g < 7) { const size_t offn = row0 + (size_t)(((g + 1) >> 2) * HALF + ((g + 1) & 3) * 16) * ldc;
; #pragma unroll
;                 for (int bj = 0; bj < 2; ++bj)
; #pragma unroll
;                     for (int n = 0; n < 2; ++n) bs[(g + 1) & 1][bj][n] = *(const f32x4*)(base + offn + bj * HALF + 4 * n); }
; #pragma unroll
;             for (int bj = 0; bj < 2; ++bj) { const f32x4 v0 = bs[g & 1][bj][0] + gv[bj][0] * acc[ai][bj][m][0], v1 = bs[g & 1][bj][1] + gv[bj][1] * acc[ai][bj][m][1];
;                 u32x4 w; w.x = cvt_pk_bf16(v0[0], v0[1]); w.y = cvt_pk_bf16(v0[2], v0[3]); w.z = cvt_pk_bf16(v1[0], v1[1]); w.w = cvt_pk_bf16(v1[2], v1[3]);
;                 *(u32x4*)(out + off + bj * HALF) = w; }
;         }
;     }
.LBB0_1762:
	s_ashr_i32 s21, s28, 31
	s_lshr_b32 s21, s21, 28
	s_add_i32 s21, s28, s21
	s_ashr_i32 s21, s21, 4
	v_lshl_add_u32 v164, s28, 8, v1
	v_lshl_or_b32 v162, s29, 8, v167
	s_mul_hi_i32 s23, s21, 0x18000
	s_mul_i32 s21, s21, 0x18000
	v_ashrrev_i32_e32 v165, 31, v164
	s_add_u32 s30, s45, s21
	v_ashrrev_i32_e32 v163, 31, v162
	v_lshlrev_b64 v[164:165], 12, v[164:165]
	v_readlane_b32 s60, v252, 2
	s_addc_u32 s31, s46, s23
	v_lshl_add_u64 v[164:165], v[164:165], 0, v[162:163]
	v_readlane_b32 s61, v252, 3
	v_lshl_add_u64 v[70:71], v[162:163], 2, s[30:31]
	global_load_dwordx4 v[74:77], v[70:71], off offset:16 nt
	global_load_dwordx4 v[78:81], v[70:71], off nt
	global_load_dwordx4 v[66:69], v[70:71], off offset:528 nt
	s_nop 0
	global_load_dwordx4 v[70:73], v[70:71], off offset:512 nt
	v_lshl_add_u64 v[162:163], v[164:165], 2, s[60:61]
	global_load_dwordx4 v[172:175], v[162:163], off offset:16 nt
	global_load_dwordx4 v[176:179], v[162:163], off nt
	global_load_dwordx4 v[180:183], v[162:163], off offset:528 nt
	global_load_dwordx4 v[184:187], v[162:163], off offset:512 nt
	s_mov_b64 s[28:29], 0x40000
	v_add_co_u32_e32 v196, vcc, s52, v162
	v_lshl_add_u64 v[192:193], v[162:163], 0, s[28:29]
	s_nop 0
	v_addc_co_u32_e32 v197, vcc, 0, v163, vcc
	global_load_dwordx4 v[188:191], v[196:197], off nt
	s_nop 0
	global_load_dwordx4 v[192:195], v[192:193], off offset:16 nt
	s_mov_b64 s[28:29], 0x40200
	v_lshl_add_u64 v[200:201], v[162:163], 0, s[28:29]
	global_load_dwordx4 v[196:199], v[196:197], off offset:512 nt
	s_nop 0
	global_load_dwordx4 v[200:203], v[200:201], off offset:16 nt
	v_readlane_b32 s28, v252, 46
	v_readlane_b32 s29, v252, 47
	s_mov_b32 s21, 0x80000
	v_readlane_b32 s62, v252, 4
	v_lshl_add_u64 v[164:165], v[164:165], 1, s[28:29]
	s_mov_b64 s[28:29], 0x80000
	v_readlane_b32 s63, v252, 5
	v_readlane_b32 s64, v252, 6
	v_readlane_b32 s65, v252, 7
	v_readlane_b32 s66, v252, 8
	v_readlane_b32 s67, v252, 9
	v_readlane_b32 s68, v252, 10
	v_readlane_b32 s69, v252, 11
	v_readlane_b32 s70, v252, 12
	v_readlane_b32 s71, v252, 13
	v_readlane_b32 s72, v252, 14
	v_readlane_b32 s73, v252, 15
	v_readlane_b32 s74, v252, 16
	v_readlane_b32 s75, v252, 17
	s_waitcnt vmcnt(0)
	v_pk_fma_f32 v[174:175], v[140:141], v[76:77], v[174:175]
	v_pk_fma_f32 v[144:145], v[144:145], v[80:81], v[178:179]
	v_pk_fma_f32 v[142:143], v[142:143], v[78:79], v[176:177]
	v_pk_fma_f32 v[140:141], v[138:139], v[74:75], v[172:173]
	v_cvt_pk_bf16_f32 v138, v142, v143
	v_cvt_pk_bf16_f32 v139, v144, v145
	v_pk_fma_f32 v[136:137], v[136:137], v[72:73], v[186:187]
	v_cvt_pk_bf16_f32 v140, v140, v141
	v_cvt_pk_bf16_f32 v141, v174, v175
	global_store_dwordx4 v[164:165], v[138:141], off
	v_pk_fma_f32 v[134:135], v[134:135], v[70:71], v[184:185]
	v_pk_fma_f32 v[126:127], v[126:127], v[78:79], v[188:189]
	v_pk_fma_f32 v[138:139], v[132:133], v[68:69], v[182:183]
	v_pk_fma_f32 v[132:133], v[130:131], v[66:67], v[180:181]
	v_cvt_pk_bf16_f32 v130, v134, v135
	v_cvt_pk_bf16_f32 v131, v136, v137
	v_pk_fma_f32 v[172:173], v[124:125], v[76:77], v[194:195]
	v_cvt_pk_bf16_f32 v132, v132, v133
	v_cvt_pk_bf16_f32 v133, v138, v139
	global_store_dwordx4 v[164:165], v[130:133], off offset:256
	v_pk_fma_f32 v[124:125], v[122:123], v[74:75], v[192:193]
	v_pk_fma_f32 v[128:129], v[128:129], v[80:81], v[190:191]
	v_add_co_u32_e32 v132, vcc, s21, v162
	v_lshl_add_u64 v[130:131], v[162:163], 0, s[28:29]
	s_nop 0
	v_addc_co_u32_e32 v133, vcc, 0, v163, vcc
	global_load_dwordx4 v[142:145], v[132:133], off nt
	global_load_dwordx4 v[138:141], v[130:131], off offset:16 nt
	s_mov_b64 s[28:29], 0x80200
	v_lshl_add_u64 v[130:131], v[162:163], 0, s[28:29]
	s_mov_b32 s21, 0x20000
	global_load_dwordx4 v[134:137], v[132:133], off offset:512 nt
	s_nop 0
	global_load_dwordx4 v[130:133], v[130:131], off offset:16 nt
	v_cvt_pk_bf16_f32 v122, v126, v127
	v_add_co_u32_e32 v126, vcc, s21, v164
	v_cvt_pk_bf16_f32 v123, v128, v129
	v_cvt_pk_bf16_f32 v124, v124, v125
	v_cvt_pk_bf16_f32 v125, v172, v173
	s_mov_b32 s21, 0xc0000
	s_nop 0
	v_addc_co_u32_e32 v127, vcc, 0, v165, vcc
	global_store_dwordx4 v[126:127], v[122:125], off
	v_pk_fma_f32 v[120:121], v[120:121], v[72:73], v[198:199]
	v_pk_fma_f32 v[118:119], v[118:119], v[70:71], v[196:197]
	v_pk_fma_f32 v[122:123], v[116:117], v[68:69], v[202:203]
	v_pk_fma_f32 v[116:117], v[114:115], v[66:67], v[200:201]
	v_cvt_pk_bf16_f32 v114, v118, v119
	v_cvt_pk_bf16_f32 v115, v120, v121
	s_mov_b64 s[28:29], 0xc0000
	v_cvt_pk_bf16_f32 v116, v116, v117
	v_cvt_pk_bf16_f32 v117, v122, v123
	v_add_co_u32_e32 v122, vcc, s21, v162
	global_store_dwordx4 v[126:127], v[114:117], off offset:256
	v_lshl_add_u64 v[118:119], v[162:163], 0, s[28:29]
	v_addc_co_u32_e32 v123, vcc, 0, v163, vcc
	global_load_dwordx4 v[114:117], v[122:123], off nt
	s_nop 0
	global_load_dwordx4 v[118:121], v[118:119], off offset:16 nt
	s_mov_b64 s[28:29], 0xc0200
	v_lshl_add_u64 v[126:127], v[162:163], 0, s[28:29]
	global_load_dwordx4 v[122:125], v[122:123], off offset:512 nt
	s_nop 0
	global_load_dwordx4 v[126:129], v[126:127], off offset:16 nt
	s_mov_b32 s21, 0x200000
	s_mov_b64 s[28:29], 0x200000
	s_waitcnt vmcnt(9)
	v_pk_fma_f32 v[110:111], v[110:111], v[78:79], v[142:143]
	s_waitcnt vmcnt(8)
	v_pk_fma_f32 v[140:141], v[108:109], v[76:77], v[140:141]
	v_pk_fma_f32 v[108:109], v[106:107], v[74:75], v[138:139]
	v_cvt_pk_bf16_f32 v106, v110, v111
	v_add_co_u32_e32 v110, vcc, s52, v164
	v_pk_fma_f32 v[112:113], v[112:113], v[80:81], v[144:145]
	s_nop 0
	v_addc_co_u32_e32 v111, vcc, 0, v165, vcc
	v_cvt_pk_bf16_f32 v107, v112, v113
	v_cvt_pk_bf16_f32 v108, v108, v109
	v_cvt_pk_bf16_f32 v109, v140, v141
	global_store_dwordx4 v[110:111], v[106:109], off
	s_waitcnt vmcnt(8)
; __device__ __forceinline__ unsigned cvt_pk_bf16(float lo, float hi) { unsigned r; asm volatile("v_cvt_pk_bf16_f32 %0, %1, %2" : "=v"(r) : "v"(lo), "v"(hi)); return r; }
;     __device__ __forceinline__ void operator()(const f32x4 (&acc)[2][2][4][2], const Unit& u, int wr, int wc, int fr, int fq) const {
;     ...
;         for (int g = 0; g < 8; ++g) { const int ai = g >> 2, m = g & 3; const size_t off = row0 + (size_t)(ai * HALF + m * 16) * ldc;
;             if (g < 7) { const size_t offn = row0 + (size_t)(((g + 1) >> 2) * HALF + ((g + 1) & 3) * 16) * ldc;
; #pragma unroll
;                 for (int bj = 0; bj < 2; ++bj)
; #pragma unroll
;                     for (int n = 0; n < 2; ++n) bs[(g + 1) & 1][bj][n] = *(const f32x4*)(base + offn + bj * HALF + 4 * n); }
; #pragma unroll
;             for (int bj = 0; bj < 2; ++bj) { const f32x4 v0 = bs[g & 1][bj][0] + gv[bj][0] * acc[ai][bj][m][0], v1 = bs[g & 1][bj][1] + gv[bj][1] * acc[ai][bj][m][1];
;                 u32x4 w; w.x = cvt_pk_bf16(v0[0], v0[1]); w.y = cvt_pk_bf16(v0[2], v0[3]); w.z = cvt_pk_bf16(v1[0], v1[1]); w.w = cvt_pk_bf16(v1[2], v1[3]);
;                 *(u32x4*)(out + off + bj * HALF) = w; }
;         }
	v_pk_fma_f32 v[104:105], v[104:105], v[72:73], v[136:137]
	v_pk_fma_f32 v[102:103], v[102:103], v[70:71], v[134:135]
	s_waitcnt vmcnt(7)
	v_pk_fma_f32 v[106:107], v[100:101], v[68:69], v[132:133]
	v_pk_fma_f32 v[100:101], v[98:99], v[66:67], v[130:131]
	v_cvt_pk_bf16_f32 v98, v102, v103
	v_cvt_pk_bf16_f32 v99, v104, v105
	s_waitcnt vmcnt(4)
	v_pk_fma_f32 v[94:95], v[94:95], v[78:79], v[114:115]
	v_cvt_pk_bf16_f32 v100, v100, v101
	v_cvt_pk_bf16_f32 v101, v106, v107
	global_store_dwordx4 v[110:111], v[98:101], off offset:256
	s_waitcnt vmcnt(4)
	v_pk_fma_f32 v[114:115], v[92:93], v[76:77], v[120:121]
	v_pk_fma_f32 v[92:93], v[90:91], v[74:75], v[118:119]
	v_add_co_u32_e32 v100, vcc, s21, v162
	v_lshl_add_u64 v[98:99], v[162:163], 0, s[28:29]
	s_nop 0
	v_addc_co_u32_e32 v101, vcc, 0, v163, vcc
	s_mov_b64 s[28:29], 0x200200
	global_load_dwordx4 v[110:113], v[100:101], off nt
	global_load_dwordx4 v[106:109], v[98:99], off offset:16 nt
	v_lshl_add_u64 v[98:99], v[162:163], 0, s[28:29]
	s_mov_b32 s21, 0x60000
	global_load_dwordx4 v[102:105], v[100:101], off offset:512 nt
	s_nop 0
	global_load_dwordx4 v[98:101], v[98:99], off offset:16 nt
	v_cvt_pk_bf16_f32 v90, v94, v95
	v_add_co_u32_e32 v94, vcc, s21, v164
	v_pk_fma_f32 v[96:97], v[96:97], v[80:81], v[116:117]
	s_nop 0
	v_addc_co_u32_e32 v95, vcc, 0, v165, vcc
	v_cvt_pk_bf16_f32 v91, v96, v97
	v_cvt_pk_bf16_f32 v92, v92, v93
	v_cvt_pk_bf16_f32 v93, v114, v115
	global_store_dwordx4 v[94:95], v[90:93], off
	s_mov_b32 s21, 0x240000
	s_waitcnt vmcnt(8)
	v_pk_fma_f32 v[88:89], v[88:89], v[72:73], v[124:125]
	s_waitcnt vmcnt(7)
	v_pk_fma_f32 v[90:91], v[84:85], v[68:69], v[128:129]
	v_pk_fma_f32 v[84:85], v[82:83], v[66:67], v[126:127]
	v_pk_fma_f32 v[86:87], v[86:87], v[70:71], v[122:123]
	s_mov_b64 s[28:29], 0x240000
	v_cvt_pk_bf16_f32 v82, v86, v87
	v_cvt_pk_bf16_f32 v83, v88, v89
	v_cvt_pk_bf16_f32 v84, v84, v85
	v_cvt_pk_bf16_f32 v85, v90, v91
	v_add_co_u32_e32 v90, vcc, s21, v162
	global_store_dwordx4 v[94:95], v[82:85], off offset:256
	v_lshl_add_u64 v[86:87], v[162:163], 0, s[28:29]
	v_addc_co_u32_e32 v91, vcc, 0, v163, vcc
	global_load_dwordx4 v[82:85], v[90:91], off nt
	s_nop 0
	global_load_dwordx4 v[86:89], v[86:87], off offset:16 nt
	v_lshl_add_u64 v[94:95], v[162:163], 0, s[10:11]
	global_load_dwordx4 v[90:93], v[90:91], off offset:512 nt
	s_nop 0
	global_load_dwordx4 v[94:97], v[94:95], off offset:16 nt
	s_mov_b64 s[28:29], -1
	s_waitcnt vmcnt(9)
	v_pk_fma_f32 v[62:63], v[62:63], v[78:79], v[110:111]
	s_waitcnt vmcnt(8)
	v_pk_fma_f32 v[108:109], v[60:61], v[76:77], v[108:109]
	v_pk_fma_f32 v[60:61], v[58:59], v[74:75], v[106:107]
	v_cvt_pk_bf16_f32 v58, v62, v63
	v_add_co_u32_e32 v62, vcc, s53, v164
	v_pk_fma_f32 v[64:65], v[64:65], v[80:81], v[112:113]
	s_nop 0
	v_addc_co_u32_e32 v63, vcc, 0, v165, vcc
	v_cvt_pk_bf16_f32 v59, v64, v65
	v_cvt_pk_bf16_f32 v60, v60, v61
	v_cvt_pk_bf16_f32 v61, v108, v109
	global_store_dwordx4 v[62:63], v[58:61], off
	s_waitcnt vmcnt(8)
	v_pk_fma_f32 v[56:57], v[56:57], v[72:73], v[104:105]
	v_pk_fma_f32 v[54:55], v[54:55], v[70:71], v[102:103]
	s_waitcnt vmcnt(7)
	v_pk_fma_f32 v[58:59], v[52:53], v[68:69], v[100:101]
	v_pk_fma_f32 v[52:53], v[50:51], v[66:67], v[98:99]
	v_cvt_pk_bf16_f32 v50, v54, v55
	v_cvt_pk_bf16_f32 v51, v56, v57
	v_lshl_add_u64 v[60:61], v[162:163], 0, s[14:15]
	v_cvt_pk_bf16_f32 v52, v52, v53
	v_cvt_pk_bf16_f32 v53, v58, v59
	v_add_co_u32_e32 v58, vcc, s54, v162
	global_store_dwordx4 v[62:63], v[50:53], off offset:256
	s_nop 0
	v_addc_co_u32_e32 v59, vcc, 0, v163, vcc
	v_lshl_add_u64 v[50:51], v[162:163], 0, s[12:13]
	global_load_dwordx4 v[54:57], v[58:59], off nt
	s_nop 0
	global_load_dwordx4 v[50:53], v[50:51], off offset:16 nt
	s_nop 0
	global_load_dwordx4 v[62:65], v[58:59], off offset:512 nt
	s_nop 0
	global_load_dwordx4 v[58:61], v[60:61], off offset:16 nt
	s_waitcnt vmcnt(9)
; __device__ __forceinline__ unsigned cvt_pk_bf16(float lo, float hi) { unsigned r; asm volatile("v_cvt_pk_bf16_f32 %0, %1, %2" : "=v"(r) : "v"(lo), "v"(hi)); return r; }
; #define PG8_BAR __builtin_amdgcn_s_barrier()
;     __device__ __forceinline__ void operator()(const f32x4 (&acc)[2][2][4][2], const Unit& u, int wr, int wc, int fr, int fq) const {
;     ...
;         for (int g = 0; g < 8; ++g) { const int ai = g >> 2, m = g & 3; const size_t off = row0 + (size_t)(ai * HALF + m * 16) * ldc;
;             if (g < 7) { const size_t offn = row0 + (size_t)(((g + 1) >> 2) * HALF + ((g + 1) & 3) * 16) * ldc;
; #pragma unroll
;                 for (int bj = 0; bj < 2; ++bj)
; #pragma unroll
;                     for (int n = 0; n < 2; ++n) bs[(g + 1) & 1][bj][n] = *(const f32x4*)(base + offn + bj * HALF + 4 * n); }
; #pragma unroll
;             for (int bj = 0; bj < 2; ++bj) { const f32x4 v0 = bs[g & 1][bj][0] + gv[bj][0] * acc[ai][bj][m][0], v1 = bs[g & 1][bj][1] + gv[bj][1] * acc[ai][bj][m][1];
;                 u32x4 w; w.x = cvt_pk_bf16(v0[0], v0[1]); w.y = cvt_pk_bf16(v0[2], v0[3]); w.z = cvt_pk_bf16(v1[0], v1[1]); w.w = cvt_pk_bf16(v1[2], v1[3]);
;                 *(u32x4*)(out + off + bj * HALF) = w; }
;         }
; template <class Epi, class Sched, bool ALIGN_EPI = false, bool SP2 = false>
; __device__ __forceinline__ void gemm_phase(PG8_LAS unsigned char* lds, const Gemm g, const Sched& S, const Epi& E) {
;     ...
;         if constexpr (!Epi::AFTER_DRAIN) { E(acc, cur, wr, wc, fr, fq); S.done(cur); }
;         if (!has_next) break;
; #pragma unroll
;         for (int a = 0; a < 2; ++a)
; #pragma unroll
;             for (int b = 0; b < 2; ++b)
; #pragma unroll
;                 for (int m = 0; m < 4; ++m)
; #pragma unroll
;                     for (int n = 0; n < 2; ++n) acc[a][b][m][n] = (f32x4){0.f, 0.f, 0.f, 0.f};
;         cur = nxt; cA = nA; cB = nB; ++ui;
;         if constexpr (ALIGN_EPI) { if (wr == 1) PG8_BAR; }
;     }
	v_pk_fma_f32 v[46:47], v[46:47], v[78:79], v[82:83]
	s_waitcnt vmcnt(8)
	v_pk_fma_f32 v[82:83], v[44:45], v[76:77], v[88:89]
	v_pk_fma_f32 v[44:45], v[42:43], v[74:75], v[86:87]
	v_cvt_pk_bf16_f32 v42, v46, v47
	v_add_co_u32_e32 v46, vcc, s55, v164
	v_pk_fma_f32 v[48:49], v[48:49], v[80:81], v[84:85]
	s_nop 0
	v_addc_co_u32_e32 v47, vcc, 0, v165, vcc
	v_cvt_pk_bf16_f32 v43, v48, v49
	v_cvt_pk_bf16_f32 v44, v44, v45
	v_cvt_pk_bf16_f32 v45, v82, v83
	global_store_dwordx4 v[46:47], v[42:45], off
	s_waitcnt vmcnt(8)
	v_pk_fma_f32 v[40:41], v[40:41], v[72:73], v[92:93]
	v_pk_fma_f32 v[38:39], v[38:39], v[70:71], v[90:91]
	s_waitcnt vmcnt(7)
	v_pk_fma_f32 v[42:43], v[36:37], v[68:69], v[96:97]
	v_pk_fma_f32 v[36:37], v[34:35], v[66:67], v[94:95]
	v_cvt_pk_bf16_f32 v34, v38, v39
	v_cvt_pk_bf16_f32 v35, v40, v41
	v_lshl_add_u64 v[38:39], v[162:163], 0, s[16:17]
	v_cvt_pk_bf16_f32 v36, v36, v37
	v_cvt_pk_bf16_f32 v37, v42, v43
	v_add_co_u32_e32 v42, vcc, s56, v162
	global_store_dwordx4 v[46:47], v[34:37], off offset:256
	s_nop 0
	v_addc_co_u32_e32 v43, vcc, 0, v163, vcc
	global_load_dwordx4 v[34:37], v[42:43], off nt
	s_nop 0
	global_load_dwordx4 v[38:41], v[38:39], off offset:16 nt
	v_lshl_add_u64 v[46:47], v[162:163], 0, s[18:19]
	global_load_dwordx4 v[42:45], v[42:43], off offset:512 nt
	s_nop 0
	global_load_dwordx4 v[46:49], v[46:47], off offset:16 nt
	s_waitcnt vmcnt(9)
	v_pk_fma_f32 v[30:31], v[30:31], v[78:79], v[54:55]
	s_waitcnt vmcnt(8)
	v_pk_fma_f32 v[52:53], v[28:29], v[76:77], v[52:53]
	v_pk_fma_f32 v[28:29], v[26:27], v[74:75], v[50:51]
	v_cvt_pk_bf16_f32 v26, v30, v31
	v_add_co_u32_e32 v30, vcc, s57, v164
	v_pk_fma_f32 v[32:33], v[32:33], v[80:81], v[56:57]
	s_nop 0
	v_addc_co_u32_e32 v31, vcc, 0, v165, vcc
	v_cvt_pk_bf16_f32 v27, v32, v33
	v_cvt_pk_bf16_f32 v28, v28, v29
	v_cvt_pk_bf16_f32 v29, v52, v53
	global_store_dwordx4 v[30:31], v[26:29], off
	s_waitcnt vmcnt(8)
	v_pk_fma_f32 v[16:17], v[16:17], v[72:73], v[64:65]
	v_pk_fma_f32 v[14:15], v[14:15], v[70:71], v[62:63]
	s_waitcnt vmcnt(7)
	v_pk_fma_f32 v[26:27], v[12:13], v[68:69], v[60:61]
	v_pk_fma_f32 v[12:13], v[10:11], v[66:67], v[58:59]
	v_cvt_pk_bf16_f32 v10, v14, v15
	v_cvt_pk_bf16_f32 v11, v16, v17
	s_waitcnt vmcnt(3)
	v_pk_fma_f32 v[14:15], v[20:21], v[76:77], v[40:41]
	v_cvt_pk_bf16_f32 v12, v12, v13
	v_cvt_pk_bf16_f32 v13, v26, v27
	global_store_dwordx4 v[30:31], v[10:13], off offset:256
	v_pk_fma_f32 v[16:17], v[18:19], v[74:75], v[38:39]
	s_waitcnt vmcnt(3)
	v_pk_fma_f32 v[8:9], v[8:9], v[72:73], v[44:45]
	v_pk_fma_f32 v[12:13], v[24:25], v[80:81], v[36:37]
	v_pk_fma_f32 v[10:11], v[22:23], v[78:79], v[34:35]
	v_pk_fma_f32 v[6:7], v[6:7], v[70:71], v[42:43]
	v_cvt_pk_bf16_f32 v10, v10, v11
	v_cvt_pk_bf16_f32 v11, v12, v13
	v_cvt_pk_bf16_f32 v12, v16, v17
	v_cvt_pk_bf16_f32 v13, v14, v15
	v_add_co_u32_e32 v14, vcc, s58, v164
	s_nop 1
	v_addc_co_u32_e32 v15, vcc, 0, v165, vcc
	global_store_dwordx4 v[14:15], v[10:13], off
	s_andn2_b64 vcc, exec, s[0:1]
	s_waitcnt vmcnt(3)
	v_pk_fma_f32 v[10:11], v[4:5], v[68:69], v[48:49]
	v_pk_fma_f32 v[4:5], v[2:3], v[66:67], v[46:47]
	v_cvt_pk_bf16_f32 v2, v6, v7
	v_cvt_pk_bf16_f32 v3, v8, v9
	s_nop 0
	v_cvt_pk_bf16_f32 v4, v4, v5
	v_cvt_pk_bf16_f32 v5, v10, v11
	global_store_dwordx4 v[14:15], v[2:5], off offset:256
	s_cbranch_vccnz .LBB0_1751
	s_andn2_b64 vcc, exec, s[4:5]
	s_cbranch_vccnz .LBB0_1750
	s_barrier
	s_branch .LBB0_1750

;     __device__ __forceinline__ void operator()(const f32x4 (&acc)[2][2][4][2], const Unit& u, int wr, int wc, int fr, int fq) const {
;         const int col0 = u.pn * BM + wc * 32 + 8 * fq;
;         const int b = (u.pm * BM) / rows_per_batch;
;         const float* gp = gate + (size_t)b * gate_stride + col0;
;         f32x4 gv[2][2];
; #pragma unroll
;         for (int bj = 0; bj < 2; ++bj)
; #pragma unroll
;             for (int n = 0; n < 2; ++n) gv[bj][n] = *(const f32x4*)(gp + bj * HALF + 4 * n);
;         const size_t row0 = (size_t)(u.pm * BM + wr * 64 + fr) * ldc + col0;
;         u32x4 bs[2][2];
; #pragma unroll
;         for (int bj = 0; bj < 2; ++bj) bs[0][bj] = *(const u32x4*)(base + row0 + bj * HALF);
; #pragma unroll
;         for (int g = 0; g < 8; ++g) { const int ai = g >> 2, m = g & 3; const size_t off = row0 + (size_t)(ai * HALF + m * 16) * ldc;
;             if (g < 7) { const size_t offn = row0 + (size_t)(((g + 1) >> 2) * HALF + ((g + 1) & 3) * 16) * ldc;
; #pragma unroll
;                 for (int bj = 0; bj < 2; ++bj) bs[(g + 1) & 1][bj] = *(const u32x4*)(base + offn + bj * HALF); }
; #pragma unroll
;             for (int bj = 0; bj < 2; ++bj) { const u32x4 w = bs[g & 1][bj];
;                 const f32x4 x0 = {__builtin_bit_cast(float, w.x << 16), __builtin_bit_cast(float, w.x & 0xffff0000u), __builtin_bit_cast(float, w.y << 16), __builtin_bit_cast(float, w.y & 0xffff0000u)};
;                 const f32x4 x1 = {__builtin_bit_cast(float, w.z << 16), __builtin_bit_cast(float, w.z & 0xffff0000u), __builtin_bit_cast(float, w.w << 16), __builtin_bit_cast(float, w.w & 0xffff0000u)};
;                 *(f32x4*)(out + off + bj * HALF) = x0 + gv[bj][0] * acc[ai][bj][m][0];
;                 *(f32x4*)(out + off + bj * HALF + 4) = x1 + gv[bj][1] * acc[ai][bj][m][1]; }
;         }
;     }
.LBB0_2168:
	v_lshl_add_u32 v130, s53, 8, v164
	v_lshl_or_b32 v128, s54, 8, v166
	v_ashrrev_i32_e32 v131, 31, v130
	v_ashrrev_i32_e32 v129, 31, v128
	v_lshlrev_b64 v[130:131], 12, v[130:131]
	v_readlane_b32 s14, v252, 46
	v_lshl_add_u64 v[160:161], v[130:131], 0, v[128:129]
	v_readlane_b32 s15, v252, 47
	s_nop 1
	v_lshl_add_u64 v[162:163], v[160:161], 1, s[14:15]
	s_ashr_i32 s14, s53, 31
	s_lshr_b32 s14, s14, 28
	s_add_i32 s14, s53, s14
	s_ashr_i32 s14, s14, 4
	s_mul_hi_i32 s15, s14, 0x18000
	s_mul_i32 s14, s14, 0x18000
	global_load_dwordx4 v[170:173], v[162:163], off nt
	global_load_dwordx4 v[174:177], v[162:163], off offset:256 nt
	s_add_u32 s14, s30, s14
	v_add_co_u32_e32 v182, vcc, s38, v162
	s_addc_u32 s15, s31, s15
	s_nop 0
	v_addc_co_u32_e32 v183, vcc, 0, v163, vcc
	v_lshl_add_u64 v[128:129], v[128:129], 2, s[14:15]
	global_load_dwordx4 v[178:181], v[182:183], off nt
	global_load_dwordx4 v[140:143], v[128:129], off nt
	global_load_dwordx4 v[136:139], v[128:129], off offset:16 nt
	global_load_dwordx4 v[132:135], v[128:129], off offset:512 nt
	s_nop 0
	global_load_dwordx4 v[128:131], v[128:129], off offset:528 nt
	s_nop 0
	global_load_dwordx4 v[182:185], v[182:183], off offset:256 nt
	v_lshl_add_u64 v[160:161], v[160:161], 2, s[80:81]
	v_add_co_u32_e32 v186, vcc, s39, v162
	s_waitcnt vmcnt(0)
	v_lshlrev_b32_e32 v192, 16, v170
	v_and_b32_e32 v193, 0xffff0000, v170
	v_lshlrev_b32_e32 v170, 16, v171
	v_and_b32_e32 v171, 0xffff0000, v171
	v_lshlrev_b32_e32 v194, 16, v172
	v_and_b32_e32 v195, 0xffff0000, v172
	v_lshlrev_b32_e32 v172, 16, v173
	v_and_b32_e32 v173, 0xffff0000, v173
	v_lshlrev_b32_e32 v196, 16, v174
	v_and_b32_e32 v197, 0xffff0000, v174
	v_lshlrev_b32_e32 v174, 16, v175
	v_and_b32_e32 v175, 0xffff0000, v175
	v_lshlrev_b32_e32 v198, 16, v176
	v_and_b32_e32 v199, 0xffff0000, v176
	v_lshlrev_b32_e32 v176, 16, v177
	v_and_b32_e32 v177, 0xffff0000, v177
	v_pk_fma_f32 v[126:127], v[126:127], v[142:143], v[170:171]
	v_pk_fma_f32 v[124:125], v[124:125], v[140:141], v[192:193]
	v_addc_co_u32_e32 v187, vcc, 0, v163, vcc
	v_pk_fma_f32 v[122:123], v[122:123], v[138:139], v[172:173]
	v_pk_fma_f32 v[120:121], v[120:121], v[136:137], v[194:195]
	v_pk_fma_f32 v[114:115], v[114:115], v[134:135], v[174:175]
	v_pk_fma_f32 v[112:113], v[112:113], v[132:133], v[196:197]
	v_pk_fma_f32 v[106:107], v[106:107], v[130:131], v[176:177]
	v_pk_fma_f32 v[104:105], v[104:105], v[128:129], v[198:199]
	global_store_dwordx4 v[160:161], v[124:127], off
	global_store_dwordx4 v[160:161], v[120:123], off offset:16
	global_store_dwordx4 v[160:161], v[112:115], off offset:512
	global_store_dwordx4 v[160:161], v[104:107], off offset:528
	v_add_co_u32_e32 v188, vcc, s39, v160
	global_load_dwordx4 v[104:107], v[186:187], off nt
	global_load_dwordx4 v[112:115], v[186:187], off offset:256 nt
	v_addc_co_u32_e32 v189, vcc, 0, v161, vcc
	v_lshlrev_b32_e32 v200, 16, v178
	v_and_b32_e32 v201, 0xffff0000, v178
	v_lshlrev_b32_e32 v178, 16, v179
	v_and_b32_e32 v179, 0xffff0000, v179
	v_add_co_u32_e32 v190, vcc, s40, v162
	v_lshlrev_b32_e32 v202, 16, v180
	v_and_b32_e32 v203, 0xffff0000, v180
	v_lshlrev_b32_e32 v120, 16, v181
	v_and_b32_e32 v121, 0xffff0000, v181
	v_lshlrev_b32_e32 v122, 16, v182
	v_and_b32_e32 v123, 0xffff0000, v182
	v_lshlrev_b32_e32 v124, 16, v183
	v_and_b32_e32 v125, 0xffff0000, v183
	v_lshlrev_b32_e32 v126, 16, v184
	v_and_b32_e32 v127, 0xffff0000, v184
	v_lshlrev_b32_e32 v170, 16, v185
	v_and_b32_e32 v171, 0xffff0000, v185
	v_pk_fma_f32 v[118:119], v[118:119], v[142:143], v[178:179]
	v_pk_fma_f32 v[116:117], v[116:117], v[140:141], v[200:201]
	v_addc_co_u32_e32 v191, vcc, 0, v163, vcc
	v_pk_fma_f32 v[110:111], v[110:111], v[138:139], v[120:121]
	v_pk_fma_f32 v[108:109], v[108:109], v[136:137], v[202:203]
	v_pk_fma_f32 v[102:103], v[102:103], v[134:135], v[124:125]
	v_pk_fma_f32 v[100:101], v[100:101], v[132:133], v[122:123]
	v_pk_fma_f32 v[98:99], v[98:99], v[130:131], v[170:171]
	v_pk_fma_f32 v[96:97], v[96:97], v[128:129], v[126:127]
	global_store_dwordx4 v[188:189], v[116:119], off
	global_store_dwordx4 v[188:189], v[108:111], off offset:16
	global_store_dwordx4 v[188:189], v[100:103], off offset:512
	global_store_dwordx4 v[188:189], v[96:99], off offset:528
	global_load_dwordx4 v[96:99], v[190:191], off nt
	s_nop 0
	global_load_dwordx4 v[100:103], v[190:191], off offset:256 nt
	v_add_co_u32_e32 v108, vcc, s41, v160
	s_waitcnt vmcnt(7)
	v_lshlrev_b32_e32 v120, 16, v104
	v_addc_co_u32_e32 v109, vcc, 0, v161, vcc
	v_add_co_u32_e32 v110, vcc, s42, v162
	v_and_b32_e32 v121, 0xffff0000, v104
	v_lshlrev_b32_e32 v104, 16, v105
	v_and_b32_e32 v105, 0xffff0000, v105
	v_addc_co_u32_e32 v111, vcc, 0, v163, vcc
	v_lshlrev_b32_e32 v122, 16, v106
	v_and_b32_e32 v123, 0xffff0000, v106
	v_lshlrev_b32_e32 v106, 16, v107
	v_and_b32_e32 v107, 0xffff0000, v107
	s_waitcnt vmcnt(6)
	v_lshlrev_b32_e32 v124, 16, v112
	v_and_b32_e32 v125, 0xffff0000, v112
	v_lshlrev_b32_e32 v112, 16, v113
	v_and_b32_e32 v113, 0xffff0000, v113
	v_lshlrev_b32_e32 v126, 16, v114
	v_and_b32_e32 v127, 0xffff0000, v114
	v_lshlrev_b32_e32 v114, 16, v115
	v_and_b32_e32 v115, 0xffff0000, v115
	v_pk_fma_f32 v[94:95], v[94:95], v[142:143], v[104:105]
	v_pk_fma_f32 v[92:93], v[92:93], v[140:141], v[120:121]
	v_add_co_u32_e32 v116, vcc, s43, v160
	v_pk_fma_f32 v[90:91], v[90:91], v[138:139], v[106:107]
	v_pk_fma_f32 v[88:89], v[88:89], v[136:137], v[122:123]
	v_pk_fma_f32 v[86:87], v[86:87], v[134:135], v[112:113]
	v_pk_fma_f32 v[84:85], v[84:85], v[132:133], v[124:125]
	v_pk_fma_f32 v[78:79], v[78:79], v[130:131], v[114:115]
	v_pk_fma_f32 v[76:77], v[76:77], v[128:129], v[126:127]
	global_store_dwordx4 v[108:109], v[92:95], off
	global_store_dwordx4 v[108:109], v[88:91], off offset:16
	global_store_dwordx4 v[108:109], v[84:87], off offset:512
	global_store_dwordx4 v[108:109], v[76:79], off offset:528
	v_addc_co_u32_e32 v117, vcc, 0, v161, vcc
	s_waitcnt vmcnt(5)
;     __device__ __forceinline__ void operator()(const f32x4 (&acc)[2][2][4][2], const Unit& u, int wr, int wc, int fr, int fq) const {
;     ...
;         for (int g = 0; g < 8; ++g) { const int ai = g >> 2, m = g & 3; const size_t off = row0 + (size_t)(ai * HALF + m * 16) * ldc;
;             if (g < 7) { const size_t offn = row0 + (size_t)(((g + 1) >> 2) * HALF + ((g + 1) & 3) * 16) * ldc;
; #pragma unroll
;                 for (int bj = 0; bj < 2; ++bj) bs[(g + 1) & 1][bj] = *(const u32x4*)(base + offn + bj * HALF); }
; #pragma unroll
;             for (int bj = 0; bj < 2; ++bj) { const u32x4 w = bs[g & 1][bj];
;                 const f32x4 x0 = {__builtin_bit_cast(float, w.x << 16), __builtin_bit_cast(float, w.x & 0xffff0000u), __builtin_bit_cast(float, w.y << 16), __builtin_bit_cast(float, w.y & 0xffff0000u)};
;                 const f32x4 x1 = {__builtin_bit_cast(float, w.z << 16), __builtin_bit_cast(float, w.z & 0xffff0000u), __builtin_bit_cast(float, w.w << 16), __builtin_bit_cast(float, w.w & 0xffff0000u)};
;                 *(f32x4*)(out + off + bj * HALF) = x0 + gv[bj][0] * acc[ai][bj][m][0];
;                 *(f32x4*)(out + off + bj * HALF + 4) = x1 + gv[bj][1] * acc[ai][bj][m][1]; }
	v_lshlrev_b32_e32 v104, 16, v96
	v_and_b32_e32 v105, 0xffff0000, v96
	v_lshlrev_b32_e32 v96, 16, v97
	v_and_b32_e32 v97, 0xffff0000, v97
	global_load_dwordx4 v[76:79], v[110:111], off nt
	global_load_dwordx4 v[84:87], v[110:111], off offset:256 nt
	v_add_co_u32_e32 v118, vcc, s44, v162
	v_lshlrev_b32_e32 v106, 16, v98
	v_and_b32_e32 v107, 0xffff0000, v98
	v_lshlrev_b32_e32 v88, 16, v99
	v_and_b32_e32 v89, 0xffff0000, v99
	s_waitcnt vmcnt(6)
	v_lshlrev_b32_e32 v90, 16, v100
	v_and_b32_e32 v91, 0xffff0000, v100
	v_lshlrev_b32_e32 v92, 16, v101
	v_and_b32_e32 v93, 0xffff0000, v101
	v_lshlrev_b32_e32 v94, 16, v102
	v_and_b32_e32 v95, 0xffff0000, v102
	v_lshlrev_b32_e32 v98, 16, v103
	v_and_b32_e32 v99, 0xffff0000, v103
	v_pk_fma_f32 v[82:83], v[82:83], v[142:143], v[96:97]
	v_pk_fma_f32 v[80:81], v[80:81], v[140:141], v[104:105]
	v_addc_co_u32_e32 v119, vcc, 0, v163, vcc
	v_pk_fma_f32 v[74:75], v[74:75], v[138:139], v[88:89]
	v_pk_fma_f32 v[72:73], v[72:73], v[136:137], v[106:107]
	v_pk_fma_f32 v[70:71], v[70:71], v[134:135], v[92:93]
	v_pk_fma_f32 v[68:69], v[68:69], v[132:133], v[90:91]
	v_pk_fma_f32 v[66:67], v[66:67], v[130:131], v[98:99]
	v_pk_fma_f32 v[64:65], v[64:65], v[128:129], v[94:95]
	global_store_dwordx4 v[116:117], v[80:83], off
	global_store_dwordx4 v[116:117], v[72:75], off offset:16
	global_store_dwordx4 v[116:117], v[68:71], off offset:512
	global_store_dwordx4 v[116:117], v[64:67], off offset:528
	global_load_dwordx4 v[64:67], v[118:119], off nt
	s_nop 0
	global_load_dwordx4 v[68:71], v[118:119], off offset:256 nt
	v_add_co_u32_e32 v72, vcc, s45, v160
	s_waitcnt vmcnt(7)
	v_lshlrev_b32_e32 v88, 16, v76
	v_addc_co_u32_e32 v73, vcc, 0, v161, vcc
	v_add_co_u32_e32 v74, vcc, s46, v162
	v_and_b32_e32 v89, 0xffff0000, v76
	s_nop 0
	v_addc_co_u32_e32 v75, vcc, 0, v163, vcc
	v_lshlrev_b32_e32 v76, 16, v77
	v_and_b32_e32 v77, 0xffff0000, v77
	v_add_co_u32_e32 v80, vcc, s47, v160
	v_lshlrev_b32_e32 v90, 16, v78
	v_and_b32_e32 v91, 0xffff0000, v78
	v_lshlrev_b32_e32 v78, 16, v79
	v_and_b32_e32 v79, 0xffff0000, v79
	s_waitcnt vmcnt(6)
	v_lshlrev_b32_e32 v92, 16, v84
	v_and_b32_e32 v93, 0xffff0000, v84
	v_lshlrev_b32_e32 v84, 16, v85
	v_and_b32_e32 v85, 0xffff0000, v85
	v_lshlrev_b32_e32 v94, 16, v86
	v_and_b32_e32 v95, 0xffff0000, v86
	v_lshlrev_b32_e32 v86, 16, v87
	v_and_b32_e32 v87, 0xffff0000, v87
	v_pk_fma_f32 v[62:63], v[62:63], v[142:143], v[76:77]
	v_pk_fma_f32 v[60:61], v[60:61], v[140:141], v[88:89]
	v_addc_co_u32_e32 v81, vcc, 0, v161, vcc
	v_pk_fma_f32 v[58:59], v[58:59], v[138:139], v[78:79]
	v_pk_fma_f32 v[56:57], v[56:57], v[136:137], v[90:91]
	v_pk_fma_f32 v[54:55], v[54:55], v[134:135], v[84:85]
	v_pk_fma_f32 v[52:53], v[52:53], v[132:133], v[92:93]
	v_pk_fma_f32 v[46:47], v[46:47], v[130:131], v[86:87]
	v_pk_fma_f32 v[44:45], v[44:45], v[128:129], v[94:95]
	s_waitcnt vmcnt(1)
	v_lshlrev_b32_e32 v76, 16, v64
	v_and_b32_e32 v77, 0xffff0000, v64
	v_lshlrev_b32_e32 v64, 16, v65
	v_and_b32_e32 v65, 0xffff0000, v65
	global_store_dwordx4 v[72:73], v[60:63], off
	global_store_dwordx4 v[72:73], v[56:59], off offset:16
	global_store_dwordx4 v[72:73], v[52:55], off offset:512
	global_store_dwordx4 v[72:73], v[44:47], off offset:528
	v_add_co_u32_e32 v82, vcc, s48, v162
	v_lshlrev_b32_e32 v78, 16, v66
	v_and_b32_e32 v79, 0xffff0000, v66
	global_load_dwordx4 v[44:47], v[74:75], off nt
	global_load_dwordx4 v[52:55], v[74:75], off offset:256 nt
	v_lshlrev_b32_e32 v56, 16, v67
	v_and_b32_e32 v57, 0xffff0000, v67
	s_waitcnt vmcnt(6)
;     __device__ __forceinline__ void operator()(const f32x4 (&acc)[2][2][4][2], const Unit& u, int wr, int wc, int fr, int fq) const {
;     ...
;         for (int g = 0; g < 8; ++g) { const int ai = g >> 2, m = g & 3; const size_t off = row0 + (size_t)(ai * HALF + m * 16) * ldc;
;             if (g < 7) { const size_t offn = row0 + (size_t)(((g + 1) >> 2) * HALF + ((g + 1) & 3) * 16) * ldc;
; #pragma unroll
;                 for (int bj = 0; bj < 2; ++bj) bs[(g + 1) & 1][bj] = *(const u32x4*)(base + offn + bj * HALF); }
; #pragma unroll
;             for (int bj = 0; bj < 2; ++bj) { const u32x4 w = bs[g & 1][bj];
;                 const f32x4 x0 = {__builtin_bit_cast(float, w.x << 16), __builtin_bit_cast(float, w.x & 0xffff0000u), __builtin_bit_cast(float, w.y << 16), __builtin_bit_cast(float, w.y & 0xffff0000u)};
;                 const f32x4 x1 = {__builtin_bit_cast(float, w.z << 16), __builtin_bit_cast(float, w.z & 0xffff0000u), __builtin_bit_cast(float, w.w << 16), __builtin_bit_cast(float, w.w & 0xffff0000u)};
;                 *(f32x4*)(out + off + bj * HALF) = x0 + gv[bj][0] * acc[ai][bj][m][0];
;                 *(f32x4*)(out + off + bj * HALF + 4) = x1 + gv[bj][1] * acc[ai][bj][m][1]; }
	v_lshlrev_b32_e32 v58, 16, v68
	v_and_b32_e32 v59, 0xffff0000, v68
	v_lshlrev_b32_e32 v60, 16, v69
	v_and_b32_e32 v61, 0xffff0000, v69
	v_lshlrev_b32_e32 v62, 16, v70
	v_and_b32_e32 v63, 0xffff0000, v70
	v_lshlrev_b32_e32 v66, 16, v71
	v_and_b32_e32 v67, 0xffff0000, v71
	v_pk_fma_f32 v[50:51], v[50:51], v[142:143], v[64:65]
	v_pk_fma_f32 v[48:49], v[48:49], v[140:141], v[76:77]
	v_addc_co_u32_e32 v83, vcc, 0, v163, vcc
	v_pk_fma_f32 v[42:43], v[42:43], v[138:139], v[56:57]
	v_pk_fma_f32 v[40:41], v[40:41], v[136:137], v[78:79]
	v_pk_fma_f32 v[38:39], v[38:39], v[134:135], v[60:61]
	v_pk_fma_f32 v[36:37], v[36:37], v[132:133], v[58:59]
	v_pk_fma_f32 v[34:35], v[34:35], v[130:131], v[66:67]
	v_pk_fma_f32 v[32:33], v[32:33], v[128:129], v[62:63]
	global_store_dwordx4 v[80:81], v[48:51], off
	global_store_dwordx4 v[80:81], v[40:43], off offset:16
	global_store_dwordx4 v[80:81], v[36:39], off offset:512
	global_store_dwordx4 v[80:81], v[32:35], off offset:528
	global_load_dwordx4 v[32:35], v[82:83], off nt
	s_nop 0
	global_load_dwordx4 v[36:39], v[82:83], off offset:256 nt
	v_add_co_u32_e32 v40, vcc, s49, v160
	s_waitcnt vmcnt(7)
	v_lshlrev_b32_e32 v48, 16, v44
	v_addc_co_u32_e32 v41, vcc, 0, v161, vcc
	v_add_co_u32_e32 v42, vcc, s50, v160
	v_and_b32_e32 v49, 0xffff0000, v44
	v_lshlrev_b32_e32 v44, 16, v45
	v_and_b32_e32 v45, 0xffff0000, v45
	s_waitcnt vmcnt(6)
	v_lshlrev_b32_e32 v58, 16, v54
	v_and_b32_e32 v59, 0xffff0000, v54
	v_lshlrev_b32_e32 v54, 16, v55
	v_and_b32_e32 v55, 0xffff0000, v55
	v_addc_co_u32_e32 v43, vcc, 0, v161, vcc
	v_lshlrev_b32_e32 v50, 16, v46
	v_and_b32_e32 v51, 0xffff0000, v46
	v_lshlrev_b32_e32 v46, 16, v47
	v_and_b32_e32 v47, 0xffff0000, v47
	v_lshlrev_b32_e32 v56, 16, v52
	v_and_b32_e32 v57, 0xffff0000, v52
	v_lshlrev_b32_e32 v52, 16, v53
	v_and_b32_e32 v53, 0xffff0000, v53
	v_pk_fma_f32 v[30:31], v[30:31], v[142:143], v[44:45]
	v_pk_fma_f32 v[28:29], v[28:29], v[140:141], v[48:49]
	v_pk_fma_f32 v[10:11], v[10:11], v[130:131], v[54:55]
	v_pk_fma_f32 v[8:9], v[8:9], v[128:129], v[58:59]
	s_waitcnt vmcnt(1)
	v_lshlrev_b32_e32 v44, 16, v32
	v_and_b32_e32 v45, 0xffff0000, v32
	v_lshlrev_b32_e32 v32, 16, v33
	v_and_b32_e32 v33, 0xffff0000, v33
	s_and_b64 vcc, exec, s[0:1]
	v_pk_fma_f32 v[26:27], v[26:27], v[138:139], v[46:47]
	v_pk_fma_f32 v[24:25], v[24:25], v[136:137], v[50:51]
	v_pk_fma_f32 v[18:19], v[18:19], v[134:135], v[52:53]
	v_pk_fma_f32 v[16:17], v[16:17], v[132:133], v[56:57]
	v_lshlrev_b32_e32 v46, 16, v34
	v_and_b32_e32 v47, 0xffff0000, v34
	v_lshlrev_b32_e32 v34, 16, v35
	v_and_b32_e32 v35, 0xffff0000, v35
	s_waitcnt vmcnt(0)
	v_lshlrev_b32_e32 v48, 16, v36
	v_and_b32_e32 v49, 0xffff0000, v36
	v_lshlrev_b32_e32 v36, 16, v37
	v_and_b32_e32 v37, 0xffff0000, v37
	v_lshlrev_b32_e32 v50, 16, v38
	v_and_b32_e32 v51, 0xffff0000, v38
	v_lshlrev_b32_e32 v38, 16, v39
	v_and_b32_e32 v39, 0xffff0000, v39
	global_store_dwordx4 v[40:41], v[28:31], off
	global_store_dwordx4 v[40:41], v[24:27], off offset:16
	global_store_dwordx4 v[40:41], v[16:19], off offset:512
	global_store_dwordx4 v[40:41], v[8:11], off offset:528
	s_mov_b64 s[0:1], -1
	v_pk_fma_f32 v[14:15], v[14:15], v[138:139], v[34:35]
	v_pk_fma_f32 v[10:11], v[22:23], v[142:143], v[32:33]
	v_pk_fma_f32 v[8:9], v[20:21], v[140:141], v[44:45]
	v_pk_fma_f32 v[12:13], v[12:13], v[136:137], v[46:47]
	v_pk_fma_f32 v[6:7], v[6:7], v[134:135], v[36:37]
	v_pk_fma_f32 v[4:5], v[4:5], v[132:133], v[48:49]
	v_pk_fma_f32 v[2:3], v[2:3], v[130:131], v[38:39]
	v_pk_fma_f32 v[0:1], v[0:1], v[128:129], v[50:51]
	global_store_dwordx4 v[42:43], v[8:11], off
	global_store_dwordx4 v[42:43], v[12:15], off offset:16
	global_store_dwordx4 v[42:43], v[4:7], off offset:512
	global_store_dwordx4 v[42:43], v[0:3], off offset:528
	s_cbranch_vccnz .LBB0_2153
	s_andn2_b64 vcc, exec, s[6:7]
	s_cbranch_vccnz .LBB0_2152
	s_barrier
	s_branch .LBB0_2152
